# P6 LoRA and LRU-gate GEMMs: K loop restricted to the 128-wide non-zero window of the block-structured weights (one 2-tile iteration instead of two)
# speedup vs baseline: 1.0105x; 1.0105x over previous
; #define PG8_STAGE(bufoff, gbase, voff) do { _Pragma("unroll") for (int _i = 0; _i < 2; ++_i) \
;         __builtin_amdgcn_global_load_lds((const unsigned*)((const char*)(gbase) + (voff)[_i]), (LAS unsigned*)(lds + (bufoff) + ldsw + _i * 8192), 16, 0, 0); } while (0)
; #define PG8_WAIT_V(n) asm volatile("s_waitcnt vmcnt(" #n ")" ::: "memory")
; #define PG8_BAR __builtin_amdgcn_s_barrier()
;     __device__ __forceinline__ long aoff(const Unit& u) const {
;         long o = (long)u.pm * 256 * lda;
;         if (mode == 1) o += 256 * (u.pn >> 1); else if (mode >= 2) o += u.pn * 256;
;         return o;
;     }
;     __device__ __forceinline__ long boff(const Unit& u) const {
;         if (mode == 2) return (long)(u.pm >> 3) * 256 * ldb + u.pn * 256;
;         if (mode == 3) return (long)u.pn * 256 * ldb + (u.pm >> 3) * 256;
;         return (long)u.pn * 256 * ldb;
; template <class Epi>
; __device__ __forceinline__ void gemm_phase(LAS unsigned char* lds, const Gemm g, const Sched& S, const Epi& E) {
;     ...
;     const char* cA = (const char*)g.A + (size_t)S.aoff(cur) * 2; const char* cB = (const char*)g.Bt + (size_t)S.boff(cur) * 2;
;     PG8_STAGE(PG8_SB(0, 0), cB, voffB); PG8_STAGE(PG8_SB(0, 1), cB + hstepB, voffB); PG8_STAGE(PG8_SA(0, 0), cA, voffA); PG8_STAGE(PG8_SA(0, 1), cA + hstepA, voffA);
;     if (wr == 1) PG8_BAR;
;     PG8_WAIT_V(2); PG8_BAR;
;     PG8_STAGE(PG8_SB(1, 0), cB + kstep, voffB); PG8_STAGE(PG8_SA(1, 0), cA + kstep, voffA); PG8_STAGE(PG8_SB(1, 1), cB + hstepB + kstep, voffB);
;     PG8_WAIT_V(6); PG8_BAR;
.LBB0_764:
	s_add_u32 s30, s34, 0x2c00000
	s_addc_u32 s31, s35, 0
	s_add_u32 s80, s34, 0x18b00000
	s_addc_u32 s92, s35, 0
	s_add_u32 s68, s34, 0x1ee00000
	s_addc_u32 s69, s35, 0
	s_andn2_b64 vcc, exec, s[0:1]
	v_writelane_b32 v228, s96, 0
	s_nop 1
	v_writelane_b32 v228, s97, 1
	s_cbranch_vccnz .LBB0_880
	v_bfe_i32 v2, v8, 27, 1
	v_lshlrev_b32_e32 v0, 4, v8
	v_lshrrev_b32_e32 v2, 22, v2
	v_add_u32_e32 v2, v0, v2
	v_and_b32_e32 v2, 0xfffffc00, v2
	v_sub_u32_e32 v2, v0, v2
	v_ashrrev_i32_e32 v1, 31, v8
	v_lshrrev_b32_e32 v3, 4, v2
	v_lshrrev_b32_e32 v1, 26, v1
	v_bitop3_b32 v3, v3, v2, 32 bitop3:0x6c
	v_ashrrev_i32_e32 v2, 31, v2
	v_add_u32_e32 v1, v8, v1
	v_lshrrev_b32_e32 v2, 26, v2
	v_ashrrev_i32_e32 v1, 6, v1
	v_add_u32_e32 v2, v3, v2
	v_lshlrev_b32_e32 v4, 3, v1
	v_ashrrev_i32_e32 v2, 6, v2
	v_and_b32_e32 v4, -16, v4
	v_mul_i32_i24_e32 v5, 64, v2
	v_add_u32_e32 v4, v2, v4
	v_sub_u32_e32 v3, v3, v5
	v_mov_b32_e32 v5, 1
	v_lshlrev_b32_e32 v1, 5, v1
	v_ashrrev_i16_sdwa v3, v5, sext(v3) dst_sel:DWORD dst_unused:UNUSED_PAD src0_sel:DWORD src1_sel:BYTE_0
	v_lshlrev_b32_e32 v6, 1, v4
	v_lshrrev_b32_e32 v7, 2, v4
	v_and_b32_e32 v2, 3, v2
	s_mov_b32 s0, 0x7fffe0
	v_and_b32_e32 v1, 32, v1
	v_bfe_i32 v3, v3, 0, 16
	v_and_b32_e32 v6, 24, v6
	v_and_b32_e32 v7, 4, v7
	v_and_or_b32 v2, v4, s0, v2
	v_or3_b32 v2, v2, v7, v6
	v_add_lshl_u32 v1, v1, v3, 1
	v_add_u32_e32 v0, 0x2000, v0
	v_lshl_add_u32 v144, v4, 9, v1
	v_lshl_add_u32 v146, v2, 9, v1
	v_ashrrev_i32_e32 v1, 31, v0
	v_lshrrev_b32_e32 v1, 22, v1
	v_add_u32_e32 v1, v0, v1
	v_ashrrev_i32_e32 v1, 10, v1
	v_mul_i32_i24_e32 v2, 0x400, v1
	v_sub_u32_e32 v0, v0, v2
	v_lshrrev_b32_e32 v2, 4, v0
	v_bitop3_b32 v0, v2, v0, 32 bitop3:0x6c
	v_ashrrev_i32_e32 v3, 31, v0
	v_lshrrev_b32_e32 v3, 26, v3
	v_lshlrev_b32_e32 v2, 3, v1
	v_add_u32_e32 v3, v0, v3
	v_and_b32_e32 v2, -16, v2
	v_ashrrev_i32_e32 v4, 6, v3
	v_add_u32_e32 v2, v4, v2
	v_and_b32_e32 v4, 3, v4
	s_ashr_i32 s6, s8, 6
	s_ashr_i32 s5, s4, 31
	s_ashr_i32 s9, s8, 8
	v_and_or_b32 v4, v2, s0, v4
	s_lshl_b32 s15, s6, 10
	s_lshl_b64 s[0:1], s[4:5], 17
	s_add_u32 s46, s68, s0
	s_addc_u32 s47, s69, s1
	s_ashr_i32 s3, s2, 31
	v_and_b32_e32 v3, 0xc0, v3
	s_lshl_b64 s[0:1], s[2:3], 17
	v_sub_u32_e32 v0, v0, v3
	s_add_u32 s52, s30, s0
	v_lshlrev_b32_e32 v1, 5, v1
	v_ashrrev_i16_sdwa v0, v5, sext(v0) dst_sel:DWORD dst_unused:UNUSED_PAD src0_sel:DWORD src1_sel:BYTE_0
	v_lshlrev_b32_e32 v3, 1, v2
	v_lshrrev_b32_e32 v5, 2, v2
	s_addc_u32 s53, s31, s1
	s_cmp_gt_i32 s2, 7
	s_cselect_b32 s98, 0x100, 0
	s_add_u32 s46, s46, s98
	s_addc_u32 s47, s47, 0
	s_add_u32 s52, s52, s98
	s_addc_u32 s53, s53, 0
	s_add_i32 s10, s15, 0
	v_and_b32_e32 v1, 32, v1
	v_bfe_i32 v0, v0, 0, 16
	v_and_b32_e32 v3, 24, v3
	v_and_b32_e32 v5, 4, v5
	s_add_i32 m0, s10, 0x10000
	v_or3_b32 v3, v4, v5, v3
	v_add_lshl_u32 v0, v1, v0, 1
	global_load_lds_dwordx4 v146, s[52:53]
	s_add_i32 m0, s10, 0x12000
	v_lshl_add_u32 v150, v3, 9, v0
	s_add_u32 s0, s52, 0x10000
	global_load_lds_dwordx4 v150, s[52:53]
	s_addc_u32 s1, s53, 0
	s_add_i32 m0, s10, 0x14000
	s_add_i32 s89, s10, 0x2000
	global_load_lds_dwordx4 v146, s[0:1]
	s_add_i32 m0, s10, 0x16000
	v_lshl_add_u32 v148, v2, 9, v0
	global_load_lds_dwordx4 v150, s[0:1]
	s_mov_b32 m0, s10
	s_add_u32 s0, s46, 0x10000
	global_load_lds_dwordx4 v144, s[46:47]
	s_mov_b32 m0, s89
	s_addc_u32 s1, s47, 0
	s_add_i32 s90, s10, 0x4000
	global_load_lds_dwordx4 v148, s[46:47]
	s_mov_b32 m0, s90
	s_add_i32 s91, s10, 0x6000
	global_load_lds_dwordx4 v144, s[0:1]
	s_mov_b32 m0, s91
	v_mov_b32_e32 v153, 0
	global_load_lds_dwordx4 v148, s[0:1]
	v_mov_b32_e32 v147, v153
	v_mov_b32_e32 v151, v153
	v_mov_b32_e32 v145, v153
	v_mov_b32_e32 v149, v153
	s_cmp_eq_u32 s9, 1
	s_mov_b64 s[84:85], s[94:95]
	s_mov_b32 s93, 0
	v_lshl_add_u64 v[6:7], s[52:53], 0, v[146:147]
	v_lshl_add_u64 v[4:5], s[52:53], 0, v[150:151]
	v_lshl_add_u64 v[0:1], s[46:47], 0, v[144:145]
	s_cselect_b64 s[0:1], -1, 0
	s_cmp_lg_u32 s9, 1
	v_lshl_add_u64 v[2:3], s[46:47], 0, v[148:149]
	s_cbranch_scc1 .LBB0_767
	s_barrier

; template <class Epi>
; __device__ __forceinline__ void gemm_phase(LAS unsigned char* lds, const Gemm g, const Sched& S, const Epi& E) {
;     ...
;         const bool has_next = S.next(ui + 1, nxt);
;         const char* nA = has_next ? (const char*)g.A + (size_t)S.aoff(nxt) * 2 : cA; const char* nB = has_next ? (const char*)g.Bt + (size_t)S.boff(nxt) * 2 : cB;
;     ...
;         for (int a = 0; a < 2; ++a)
; #pragma unroll
;             for (int b = 0; b < 2; ++b)
; #pragma unroll
;                 for (int m = 0; m < 4; ++m)
; #pragma unroll
;                     for (int n = 0; n < 2; ++n) acc[a][b][m][n] = (f32x4){0.f, 0.f, 0.f, 0.f};
.LBB0_772:
	s_ashr_i32 s25, s24, 31
	s_lshl_b64 s[40:41], s[24:25], 17
	s_add_u32 s40, s68, s40
	s_addc_u32 s41, s69, s41
	s_cmp_gt_i32 s26, 7
	s_cselect_b32 s98, 0x100, 0
	s_add_u32 s40, s40, s98
	s_addc_u32 s41, s41, 0
	s_and_b64 s[44:45], s[28:29], exec
	s_cselect_b32 s3, s41, s47
	s_cselect_b32 s5, s40, s46
	s_ashr_i32 s27, s26, 31
	s_lshl_b64 s[44:45], s[26:27], 17
	s_add_u32 s44, s30, s44
	s_addc_u32 s45, s31, s45
	s_add_u32 s44, s44, s98
	s_addc_u32 s45, s45, 0
	s_and_b64 s[54:55], s[28:29], exec
	v_mov_b32_e32 v0, 0
	s_cselect_b32 s25, s45, s53
	s_cselect_b32 s27, s44, s52
	s_mov_b64 s[74:75], 0
	s_mov_b64 s[54:55], 0
	s_mov_b64 s[56:57], -1
	v_mov_b32_e32 v1, v0
	v_mov_b32_e32 v2, v0
	v_mov_b32_e32 v3, v0
	v_mov_b32_e32 v4, v0
	v_mov_b32_e32 v5, v0
	v_mov_b32_e32 v6, v0
	v_mov_b32_e32 v7, v0
	v_mov_b32_e32 v8, v0
	v_mov_b32_e32 v9, v0
	v_mov_b32_e32 v10, v0
	v_mov_b32_e32 v11, v0
	v_mov_b32_e32 v12, v0
	v_mov_b32_e32 v13, v0
	v_mov_b32_e32 v14, v0
	v_mov_b32_e32 v15, v0
	v_mov_b32_e32 v16, v0
	v_mov_b32_e32 v17, v0
	v_mov_b32_e32 v18, v0
	v_mov_b32_e32 v19, v0
	v_mov_b32_e32 v20, v0
	v_mov_b32_e32 v21, v0
	v_mov_b32_e32 v22, v0
	v_mov_b32_e32 v23, v0
	v_mov_b32_e32 v24, v0
	v_mov_b32_e32 v25, v0
	v_mov_b32_e32 v26, v0
	v_mov_b32_e32 v27, v0
	v_mov_b32_e32 v28, v0
	v_mov_b32_e32 v29, v0
	v_mov_b32_e32 v30, v0
	v_mov_b32_e32 v31, v0
	v_mov_b32_e32 v64, v0
	v_mov_b32_e32 v65, v0
	v_mov_b32_e32 v66, v0
	v_mov_b32_e32 v67, v0
	v_mov_b32_e32 v68, v0
	v_mov_b32_e32 v69, v0
	v_mov_b32_e32 v70, v0
	v_mov_b32_e32 v71, v0
	v_mov_b32_e32 v72, v0
	v_mov_b32_e32 v73, v0
	v_mov_b32_e32 v74, v0
	v_mov_b32_e32 v75, v0
	v_mov_b32_e32 v76, v0
	v_mov_b32_e32 v77, v0
	v_mov_b32_e32 v78, v0
	v_mov_b32_e32 v79, v0
	v_mov_b32_e32 v88, v0
	v_mov_b32_e32 v89, v0
	v_mov_b32_e32 v90, v0
	v_mov_b32_e32 v91, v0
	v_mov_b32_e32 v92, v0
	v_mov_b32_e32 v93, v0
	v_mov_b32_e32 v94, v0
	v_mov_b32_e32 v95, v0
	v_mov_b32_e32 v96, v0
	v_mov_b32_e32 v97, v0
	v_mov_b32_e32 v98, v0
	v_mov_b32_e32 v99, v0
	v_mov_b32_e32 v100, v0
	v_mov_b32_e32 v101, v0
	v_mov_b32_e32 v102, v0
	v_mov_b32_e32 v103, v0
	v_mov_b32_e32 v32, v0
	v_mov_b32_e32 v33, v0
	v_mov_b32_e32 v34, v0
	v_mov_b32_e32 v35, v0
	v_mov_b32_e32 v36, v0
	v_mov_b32_e32 v37, v0
	v_mov_b32_e32 v38, v0
	v_mov_b32_e32 v39, v0
	v_mov_b32_e32 v40, v0
	v_mov_b32_e32 v41, v0
	v_mov_b32_e32 v42, v0
	v_mov_b32_e32 v43, v0
	v_mov_b32_e32 v44, v0
	v_mov_b32_e32 v45, v0
	v_mov_b32_e32 v46, v0
	v_mov_b32_e32 v47, v0
	v_mov_b32_e32 v48, v0
	v_mov_b32_e32 v49, v0
	v_mov_b32_e32 v50, v0
	v_mov_b32_e32 v51, v0
	v_mov_b32_e32 v52, v0
	v_mov_b32_e32 v53, v0
	v_mov_b32_e32 v54, v0
	v_mov_b32_e32 v55, v0
	v_mov_b32_e32 v56, v0
	v_mov_b32_e32 v57, v0
	v_mov_b32_e32 v58, v0
	v_mov_b32_e32 v59, v0
	v_mov_b32_e32 v60, v0
	v_mov_b32_e32 v61, v0
	v_mov_b32_e32 v62, v0
	v_mov_b32_e32 v63, v0
	v_mov_b32_e32 v104, v0
	v_mov_b32_e32 v105, v0
	v_mov_b32_e32 v106, v0
	v_mov_b32_e32 v107, v0
	v_mov_b32_e32 v108, v0
	v_mov_b32_e32 v109, v0
	v_mov_b32_e32 v110, v0
	v_mov_b32_e32 v111, v0
	v_mov_b32_e32 v112, v0
	v_mov_b32_e32 v113, v0
	v_mov_b32_e32 v114, v0
	v_mov_b32_e32 v115, v0
	v_mov_b32_e32 v116, v0
	v_mov_b32_e32 v117, v0
	v_mov_b32_e32 v118, v0
	v_mov_b32_e32 v119, v0
	v_mov_b32_e32 v120, v0
	v_mov_b32_e32 v121, v0
	v_mov_b32_e32 v122, v0
	v_mov_b32_e32 v123, v0
	v_mov_b32_e32 v124, v0
	v_mov_b32_e32 v125, v0
	v_mov_b32_e32 v126, v0
	v_mov_b32_e32 v127, v0
	v_mov_b32_e32 v128, v0
	v_mov_b32_e32 v129, v0
	v_mov_b32_e32 v130, v0
	v_mov_b32_e32 v131, v0
	v_mov_b32_e32 v132, v0
	v_mov_b32_e32 v133, v0
	v_mov_b32_e32 v134, v0
	v_mov_b32_e32 v135, v0

; #define PG8_STAGE(bufoff, gbase, voff) do { _Pragma("unroll") for (int _i = 0; _i < 2; ++_i) \
;         __builtin_amdgcn_global_load_lds((const unsigned*)((const char*)(gbase) + (voff)[_i]), (LAS unsigned*)(lds + (bufoff) + ldsw + _i * 8192), 16, 0, 0); } while (0)
; #define PG8_WAIT_V(n) asm volatile("s_waitcnt vmcnt(" #n ")" ::: "memory")
; #define PG8_BAR __builtin_amdgcn_s_barrier()
;     __device__ __forceinline__ long aoff(const Unit& u) const {
;         long o = (long)u.pm * 256 * lda;
;         if (mode == 1) o += 256 * (u.pn >> 1); else if (mode >= 2) o += u.pn * 256;
;         return o;
;     }
;     __device__ __forceinline__ long boff(const Unit& u) const {
;         if (mode == 2) return (long)(u.pm >> 3) * 256 * ldb + u.pn * 256;
;         if (mode == 3) return (long)u.pn * 256 * ldb + (u.pm >> 3) * 256;
;         return (long)u.pn * 256 * ldb;
; template <class Epi>
; __device__ __forceinline__ void gemm_phase(LAS unsigned char* lds, const Gemm g, const Sched& S, const Epi& E) {
;     ...
;     const char* cA = (const char*)g.A + (size_t)S.aoff(cur) * 2; const char* cB = (const char*)g.Bt + (size_t)S.boff(cur) * 2;
;     PG8_STAGE(PG8_SB(0, 0), cB, voffB); PG8_STAGE(PG8_SB(0, 1), cB + hstepB, voffB); PG8_STAGE(PG8_SA(0, 0), cA, voffA); PG8_STAGE(PG8_SA(0, 1), cA + hstepA, voffA);
;     if (wr == 1) PG8_BAR;
;     PG8_WAIT_V(2); PG8_BAR;
;     PG8_STAGE(PG8_SB(1, 0), cB + kstep, voffB); PG8_STAGE(PG8_SA(1, 0), cA + kstep, voffA); PG8_STAGE(PG8_SB(1, 1), cB + hstepB + kstep, voffB);
;     PG8_WAIT_V(6); PG8_BAR;
.LBB0_886:
	v_bfe_i32 v2, v8, 27, 1
	v_lshlrev_b32_e32 v0, 4, v8
	v_lshrrev_b32_e32 v2, 22, v2
	v_add_u32_e32 v2, v0, v2
	v_and_b32_e32 v2, 0xfffffc00, v2
	v_sub_u32_e32 v2, v0, v2
	v_ashrrev_i32_e32 v1, 31, v8
	v_lshrrev_b32_e32 v3, 4, v2
	v_lshrrev_b32_e32 v1, 26, v1
	v_bitop3_b32 v3, v3, v2, 32 bitop3:0x6c
	v_ashrrev_i32_e32 v2, 31, v2
	v_add_u32_e32 v1, v8, v1
	v_lshrrev_b32_e32 v2, 26, v2
	v_ashrrev_i32_e32 v1, 6, v1
	v_add_u32_e32 v2, v3, v2
	v_lshlrev_b32_e32 v4, 3, v1
	v_ashrrev_i32_e32 v2, 6, v2
	v_and_b32_e32 v4, -16, v4
	v_mul_i32_i24_e32 v5, 64, v2
	v_add_u32_e32 v4, v2, v4
	v_sub_u32_e32 v3, v3, v5
	v_mov_b32_e32 v5, 1
	v_lshlrev_b32_e32 v1, 5, v1
	v_ashrrev_i16_sdwa v3, v5, sext(v3) dst_sel:DWORD dst_unused:UNUSED_PAD src0_sel:DWORD src1_sel:BYTE_0
	v_lshlrev_b32_e32 v6, 1, v4
	v_lshrrev_b32_e32 v7, 2, v4
	v_and_b32_e32 v2, 3, v2
	s_mov_b32 s1, 0x7fffe0
	v_and_b32_e32 v1, 32, v1
	v_bfe_i32 v3, v3, 0, 16
	v_and_b32_e32 v6, 24, v6
	v_and_b32_e32 v7, 4, v7
	v_and_or_b32 v2, v4, s1, v2
	v_or3_b32 v2, v2, v7, v6
	v_add_lshl_u32 v1, v1, v3, 1
	v_add_u32_e32 v0, 0x2000, v0
	v_lshl_add_u32 v136, v4, 11, v1
	v_lshl_add_u32 v138, v2, 9, v1
	v_ashrrev_i32_e32 v1, 31, v0
	v_lshrrev_b32_e32 v1, 22, v1
	v_add_u32_e32 v1, v0, v1
	v_ashrrev_i32_e32 v1, 10, v1
	v_mul_i32_i24_e32 v2, 0x400, v1
	v_sub_u32_e32 v0, v0, v2
	v_lshrrev_b32_e32 v2, 4, v0
	v_bitop3_b32 v0, v2, v0, 32 bitop3:0x6c
	v_ashrrev_i32_e32 v3, 31, v0
	v_lshrrev_b32_e32 v3, 26, v3
	v_lshlrev_b32_e32 v2, 3, v1
	v_add_u32_e32 v3, v0, v3
	s_ashr_i32 s0, s3, 3
	v_and_b32_e32 v2, -16, v2
	v_ashrrev_i32_e32 v4, 6, v3
	v_add_u32_e32 v2, v4, v2
	v_and_b32_e32 v4, 3, v4
	s_add_i32 s0, s4, s0
	v_and_or_b32 v4, v2, s1, v4
	s_ashr_i32 s1, s0, 31
	s_lshr_b32 s1, s1, 26
	s_add_i32 s1, s0, s1
	s_ashr_i32 s4, s1, 6
	s_andn2_b32 s1, s1, 63
	s_sub_i32 s0, s0, s1
	s_bfe_i32 s1, s0, 0x80000
	s_bfe_u32 s1, s1, 0x3000c
	s_add_i32 s1, s0, s1
	s_bfe_i32 s5, s1, 0x80000
	s_sext_i32_i16 s5, s5
	s_and_b32 s1, s1, 0xf8
	s_sub_i32 s0, s0, s1
	s_ashr_i32 s61, s5, 3
	s_lshl_b32 s4, s4, 3
	s_sext_i32_i8 s0, s0
	s_lshl_b32 s1, s61, 7
	s_add_i32 s0, s4, s0
	s_and_b32 s4, s1, 0xffffff00
	s_ashr_i32 s8, s2, 6
	s_lshr_b32 s6, s5, 3
	s_ashr_i32 s1, s0, 31
	s_ashr_i32 s5, s4, 31
	s_ashr_i32 s3, s2, 8
	s_lshl_b32 s10, s8, 10
	s_lshl_b64 s[14:15], s[0:1], 19
	s_lshl_b64 s[4:5], s[4:5], 1
	s_add_u32 s1, s28, s14
	s_addc_u32 s7, s29, s15
	s_add_u32 s4, s1, s4
	s_addc_u32 s5, s7, s5
	s_bfe_i64 s[6:7], s[6:7], 0x100000
	v_and_b32_e32 v3, 0xc0, v3
	s_lshl_b64 s[6:7], s[6:7], 17
	v_sub_u32_e32 v0, v0, v3
	s_add_u32 s6, s40, s6
	v_lshlrev_b32_e32 v1, 5, v1
	v_ashrrev_i16_sdwa v0, v5, sext(v0) dst_sel:DWORD dst_unused:UNUSED_PAD src0_sel:DWORD src1_sel:BYTE_0
	v_lshlrev_b32_e32 v3, 1, v2
	v_lshrrev_b32_e32 v5, 2, v2
	s_addc_u32 s7, s41, s7
	s_bitcmp1_b32 s61, 0
	s_cselect_b32 s98, 0x100, 0
	s_add_u32 s4, s4, s98
	s_addc_u32 s5, s5, 0
	s_add_u32 s6, s6, s98
	s_addc_u32 s7, s7, 0
	s_add_i32 s11, s10, 0
	v_and_b32_e32 v1, 32, v1
	v_bfe_i32 v0, v0, 0, 16
	v_and_b32_e32 v3, 24, v3
	v_and_b32_e32 v5, 4, v5
	s_add_i32 m0, s11, 0x10000
	v_or3_b32 v3, v4, v5, v3
	v_add_lshl_u32 v0, v1, v0, 1
	global_load_lds_dwordx4 v138, s[6:7]
	s_add_i32 m0, s11, 0x12000
	v_lshl_add_u32 v142, v3, 9, v0
	s_add_u32 s14, s6, 0x10000
	global_load_lds_dwordx4 v142, s[6:7]
	s_addc_u32 s15, s7, 0
	s_add_i32 m0, s11, 0x14000
	s_add_i32 s93, s11, 0x2000
	global_load_lds_dwordx4 v138, s[14:15]
	s_add_i32 m0, s11, 0x16000
	v_lshl_add_u32 v140, v2, 11, v0
	global_load_lds_dwordx4 v142, s[14:15]
	s_mov_b32 m0, s11
	s_add_u32 s14, s4, 0x40000
	global_load_lds_dwordx4 v136, s[4:5]
	s_mov_b32 m0, s93
	s_addc_u32 s15, s5, 0
	s_add_i32 s94, s11, 0x4000
	global_load_lds_dwordx4 v140, s[4:5]
	s_mov_b32 m0, s94
	s_add_i32 s95, s11, 0x6000
	global_load_lds_dwordx4 v136, s[14:15]
	s_mov_b32 m0, s95
	v_mov_b32_e32 v139, 0
	global_load_lds_dwordx4 v140, s[14:15]
	v_mov_b32_e32 v143, v139
	v_mov_b32_e32 v137, v139
	v_mov_b32_e32 v141, v139
	s_cmp_eq_u32 s3, 1
	s_mov_b32 s96, 0
	v_lshl_add_u64 v[6:7], s[6:7], 0, v[138:139]
	v_lshl_add_u64 v[4:5], s[6:7], 0, v[142:143]
	v_lshl_add_u64 v[0:1], s[4:5], 0, v[136:137]
	s_cselect_b64 s[44:45], -1, 0
	s_cmp_lg_u32 s3, 1
	v_lshl_add_u64 v[2:3], s[4:5], 0, v[140:141]
	s_cbranch_scc1 .LBB0_888
	s_barrier

;     __device__ __forceinline__ long aoff(const Unit& u) const {
;         long o = (long)u.pm * 256 * lda;
;         if (mode == 1) o += 256 * (u.pn >> 1); else if (mode >= 2) o += u.pn * 256;
;         return o;
;     }
;     __device__ __forceinline__ long boff(const Unit& u) const {
;         if (mode == 2) return (long)(u.pm >> 3) * 256 * ldb + u.pn * 256;
;         if (mode == 3) return (long)u.pn * 256 * ldb + (u.pm >> 3) * 256;
;         return (long)u.pn * 256 * ldb;
; template <class Epi>
; __device__ __forceinline__ void gemm_phase(LAS unsigned char* lds, const Gemm g, const Sched& S, const Epi& E) {
;     ...
;         const bool has_next = S.next(ui + 1, nxt);
;         const char* nA = has_next ? (const char*)g.A + (size_t)S.aoff(nxt) * 2 : cA; const char* nB = has_next ? (const char*)g.Bt + (size_t)S.boff(nxt) * 2 : cB;
.LBB0_897:
	v_cndmask_b32_e64 v0, 0, 1, s[8:9]
	v_cmp_ne_u32_e64 s[2:3], 1, v0
	s_andn2_b64 vcc, exec, s[8:9]
	s_mov_b64 s[74:75], s[4:5]
	s_cbranch_vccnz .LBB0_899
	s_lshl_b32 s1, s56, 7
	s_and_b32 s14, s1, 0xffffff00
	s_ashr_i32 s55, s54, 31
	s_ashr_i32 s15, s14, 31
	s_lshl_b64 s[62:63], s[54:55], 19
	s_lshl_b64 s[14:15], s[14:15], 1
	s_add_u32 s1, s28, s62
	s_addc_u32 s55, s29, s63
	s_add_u32 s74, s1, s14
	s_addc_u32 s75, s55, s15
	s_bitcmp1_b32 s56, 0
	s_cselect_b32 s98, 0x100, 0
	s_add_u32 s74, s74, s98
	s_addc_u32 s75, s75, 0
.LBB0_899:
	s_ashr_i32 s57, s56, 31
	s_lshl_b64 s[14:15], s[56:57], 17
	s_add_u32 s76, s40, s14
	s_addc_u32 s77, s41, s15
	s_bitcmp1_b32 s56, 0
	s_cselect_b32 s98, 0x100, 0
	s_add_u32 s76, s76, s98
	s_addc_u32 s77, s77, 0
	s_and_b64 s[8:9], s[8:9], exec
	v_mov_b32_e32 v0, 0
	s_cselect_b32 s1, s77, s7
	s_cselect_b32 s55, s76, s6
	s_mov_b64 s[78:79], 0
	s_mov_b64 s[8:9], 0
	s_mov_b64 s[14:15], -1
	v_mov_b32_e32 v1, v0
	v_mov_b32_e32 v2, v0
	v_mov_b32_e32 v3, v0
	v_mov_b32_e32 v4, v0
	v_mov_b32_e32 v5, v0
	v_mov_b32_e32 v6, v0
	v_mov_b32_e32 v7, v0
	v_mov_b32_e32 v8, v0
	v_mov_b32_e32 v9, v0
	v_mov_b32_e32 v10, v0
	v_mov_b32_e32 v11, v0
	v_mov_b32_e32 v12, v0
	v_mov_b32_e32 v13, v0
	v_mov_b32_e32 v14, v0
	v_mov_b32_e32 v15, v0
	v_mov_b32_e32 v16, v0
	v_mov_b32_e32 v17, v0
	v_mov_b32_e32 v18, v0
	v_mov_b32_e32 v19, v0
	v_mov_b32_e32 v20, v0
	v_mov_b32_e32 v21, v0
	v_mov_b32_e32 v22, v0
	v_mov_b32_e32 v23, v0
	v_mov_b32_e32 v24, v0
	v_mov_b32_e32 v25, v0
	v_mov_b32_e32 v26, v0
	v_mov_b32_e32 v27, v0
	v_mov_b32_e32 v28, v0
	v_mov_b32_e32 v29, v0
	v_mov_b32_e32 v30, v0
	v_mov_b32_e32 v31, v0
	v_mov_b32_e32 v64, v0
	v_mov_b32_e32 v65, v0
	v_mov_b32_e32 v66, v0
	v_mov_b32_e32 v67, v0
	v_mov_b32_e32 v68, v0
	v_mov_b32_e32 v69, v0
	v_mov_b32_e32 v70, v0
	v_mov_b32_e32 v71, v0
	v_mov_b32_e32 v72, v0
	v_mov_b32_e32 v73, v0
	v_mov_b32_e32 v74, v0
	v_mov_b32_e32 v75, v0
	v_mov_b32_e32 v76, v0
	v_mov_b32_e32 v77, v0
	v_mov_b32_e32 v78, v0
	v_mov_b32_e32 v79, v0
	v_mov_b32_e32 v80, v0
	v_mov_b32_e32 v81, v0
	v_mov_b32_e32 v82, v0
	v_mov_b32_e32 v83, v0
	v_mov_b32_e32 v84, v0
	v_mov_b32_e32 v85, v0
	v_mov_b32_e32 v86, v0
	v_mov_b32_e32 v87, v0
	v_mov_b32_e32 v88, v0
	v_mov_b32_e32 v89, v0
	v_mov_b32_e32 v90, v0
	v_mov_b32_e32 v91, v0
	v_mov_b32_e32 v92, v0
	v_mov_b32_e32 v93, v0
	v_mov_b32_e32 v94, v0
	v_mov_b32_e32 v95, v0
	v_mov_b32_e32 v32, v0
	v_mov_b32_e32 v33, v0
	v_mov_b32_e32 v34, v0
	v_mov_b32_e32 v35, v0
	v_mov_b32_e32 v36, v0
	v_mov_b32_e32 v37, v0
	v_mov_b32_e32 v38, v0
	v_mov_b32_e32 v39, v0
	v_mov_b32_e32 v40, v0
	v_mov_b32_e32 v41, v0
	v_mov_b32_e32 v42, v0
	v_mov_b32_e32 v43, v0
	v_mov_b32_e32 v44, v0
	v_mov_b32_e32 v45, v0
	v_mov_b32_e32 v46, v0
	v_mov_b32_e32 v47, v0
	v_mov_b32_e32 v48, v0
	v_mov_b32_e32 v49, v0
	v_mov_b32_e32 v50, v0
	v_mov_b32_e32 v51, v0
	v_mov_b32_e32 v52, v0
	v_mov_b32_e32 v53, v0
	v_mov_b32_e32 v54, v0
	v_mov_b32_e32 v55, v0
	v_mov_b32_e32 v56, v0
	v_mov_b32_e32 v57, v0
	v_mov_b32_e32 v58, v0
	v_mov_b32_e32 v59, v0
	v_mov_b32_e32 v60, v0
	v_mov_b32_e32 v61, v0
	v_mov_b32_e32 v62, v0
	v_mov_b32_e32 v63, v0
	v_mov_b32_e32 v104, v0
	v_mov_b32_e32 v105, v0
	v_mov_b32_e32 v106, v0
	v_mov_b32_e32 v107, v0
	v_mov_b32_e32 v108, v0
	v_mov_b32_e32 v109, v0
	v_mov_b32_e32 v110, v0
	v_mov_b32_e32 v111, v0
	v_mov_b32_e32 v112, v0
	v_mov_b32_e32 v113, v0
	v_mov_b32_e32 v114, v0
	v_mov_b32_e32 v115, v0
	v_mov_b32_e32 v116, v0
	v_mov_b32_e32 v117, v0
	v_mov_b32_e32 v118, v0
	v_mov_b32_e32 v119, v0
	v_mov_b32_e32 v120, v0
	v_mov_b32_e32 v121, v0
	v_mov_b32_e32 v122, v0
	v_mov_b32_e32 v123, v0
	v_mov_b32_e32 v124, v0
	v_mov_b32_e32 v125, v0
	v_mov_b32_e32 v126, v0
	v_mov_b32_e32 v127, v0
	v_mov_b32_e32 v128, v0
	v_mov_b32_e32 v129, v0
	v_mov_b32_e32 v130, v0
	v_mov_b32_e32 v131, v0
	v_mov_b32_e32 v132, v0
	v_mov_b32_e32 v133, v0
	v_mov_b32_e32 v134, v0
	v_mov_b32_e32 v135, v0

; __global__ void __launch_bounds__(NTHR, 2) mega(Args args) {
	.amdhsa_kernel _Z4mega4Args
		.amdhsa_group_segment_fixed_size 0
		.amdhsa_private_segment_fixed_size 0
		.amdhsa_kernarg_size 592
		.amdhsa_user_sgpr_count 2
		.amdhsa_user_sgpr_dispatch_ptr 0
		.amdhsa_user_sgpr_queue_ptr 0
		.amdhsa_user_sgpr_kernarg_segment_ptr 1
		.amdhsa_user_sgpr_dispatch_id 0
		.amdhsa_user_sgpr_kernarg_preload_length 0
		.amdhsa_user_sgpr_kernarg_preload_offset 0
		.amdhsa_user_sgpr_private_segment_size 0
		.amdhsa_uses_dynamic_stack 0
		.amdhsa_enable_private_segment 0
		.amdhsa_system_sgpr_workgroup_id_x 1
		.amdhsa_system_sgpr_workgroup_id_y 0
		.amdhsa_system_sgpr_workgroup_id_z 0
		.amdhsa_system_sgpr_workgroup_info 0
		.amdhsa_system_vgpr_workitem_id 2
		.amdhsa_next_free_vgpr 230
		.amdhsa_next_free_sgpr 102
		.amdhsa_accum_offset 232
		.amdhsa_reserve_vcc 1
		.amdhsa_float_round_mode_32 0
		.amdhsa_float_round_mode_16_64 0
		.amdhsa_float_denorm_mode_32 3
		.amdhsa_float_denorm_mode_16_64 3
		.amdhsa_dx10_clamp 1
		.amdhsa_ieee_mode 1
		.amdhsa_fp16_overflow 0
		.amdhsa_tg_split 0
		.amdhsa_exception_fp_ieee_invalid_op 0
		.amdhsa_exception_fp_denorm_src 0
		.amdhsa_exception_fp_ieee_div_zero 0
		.amdhsa_exception_fp_ieee_overflow 0
		.amdhsa_exception_fp_ieee_underflow 0
		.amdhsa_exception_fp_ieee_inexact 0
		.amdhsa_exception_int_div_zero 0
	.end_amdhsa_kernel

; __global__ void __launch_bounds__(NTHR, 2) mega(Args args) {
amdhsa.kernels:
  - .agpr_count:     0
    .args:
      - .offset:         0
        .size:           336
        .value_kind:     by_value
      - .offset:         336
        .size:           4
        .value_kind:     hidden_block_count_x
      - .offset:         340
        .size:           4
        .value_kind:     hidden_block_count_y
      - .offset:         344
        .size:           4
        .value_kind:     hidden_block_count_z
      - .offset:         348
        .size:           2
        .value_kind:     hidden_group_size_x
      - .offset:         350
        .size:           2
        .value_kind:     hidden_group_size_y
      - .offset:         352
        .size:           2
        .value_kind:     hidden_group_size_z
      - .offset:         354
        .size:           2
        .value_kind:     hidden_remainder_x
      - .offset:         356
        .size:           2
        .value_kind:     hidden_remainder_y
      - .offset:         358
        .size:           2
        .value_kind:     hidden_remainder_z
      - .offset:         376
        .size:           8
        .value_kind:     hidden_global_offset_x
      - .offset:         384
        .size:           8
        .value_kind:     hidden_global_offset_y
      - .offset:         392
        .size:           8
        .value_kind:     hidden_global_offset_z
      - .offset:         400
        .size:           2
        .value_kind:     hidden_grid_dims
      - .offset:         424
        .size:           8
        .value_kind:     hidden_multigrid_sync_arg
      - .offset:         456
        .size:           4
        .value_kind:     hidden_dynamic_lds_size
    .group_segment_fixed_size: 0
    .kernarg_segment_align: 8
    .kernarg_segment_size: 592
    .language:       OpenCL C
    .language_version:
      - 2
      - 0
    .max_flat_workgroup_size: 512
    .name:           _Z4mega4Args
    .private_segment_fixed_size: 0
    .sgpr_count:     108
    .sgpr_spill_count: 68
    .symbol:         _Z4mega4Args.kd
    .uniform_work_group_size: 1
    .uses_dynamic_stack: false
    .vgpr_count:     230
    .vgpr_spill_count: 0
    .wavefront_size: 64
